# phase-0 weight transposes of the four big matrices done LDS-free: 8 rows x 8 k-chunks per wave, full 128B bf16 line writes, 16 loads in flight per wave (was 32x32 LDS tiles, one tile in flight per wor
# speedup vs baseline: 1.0187x; 1.0077x over previous
; DI int otid() { int t = threadIdx.x; asm volatile("" : "+v"(t)); return t; }
; DI void tr_phase(const float* __restrict__ src, int ld, int K, int N, u16* __restrict__ dst, char* smem, int& rot) {
;   float* tl = (float*)smem;
;   const int tid = otid();
;   const int KTn = K >> 5, NTn = N >> 5, ntiles = KTn * NTn;
;   int first = (int)blockIdx.x - rot;
;   if (first < 0) first += gridDim.x;
;   rot = (rot + ntiles) % (int)gridDim.x;
;   const int a = tid >> 5, bq = tid & 31;
;   for (int tile = first; tile < ntiles; tile += gridDim.x) {
;     const int kt = tile / NTn, nt = tile - kt * NTn;
;     __syncthreads();
; #pragma unroll
;     for (int i = 0; i < 2; ++i) tl[(a + 16 * i) * 33 + bq] = src[(size_t)(kt * 32 + a + 16 * i) * ld + nt * 32 + bq];
;     __syncthreads();
; #pragma unroll
;     for (int i = 0; i < 2; ++i) dst[(size_t)(nt * 32 + a + 16 * i) * K + kt * 32 + bq] = f2bf(tl[bq * 33 + a + 16 * i]);
;   }
; }
; DI void phase0(const Params& p, char* smem) {
;     ...
;   for (int l = 0; l < NLAYER; ++l) {
;     tr_phase(p.w_up + (size_t)l * 1024 * 5632, 5632, 1024, 5632, (u16*)(p.ws + WS_WUP) + (size_t)l * 5632 * 1024, smem, rot);
;     tr_phase(p.w_down + (size_t)l * 2816 * 1024, 1024, 2816, 1024, (u16*)(p.ws + WS_WDN) + (size_t)l * 1024 * 2816, smem, rot);
.LBB0_23:
	s_or_b64 exec, exec, s[0:1]
	v_readlane_b32 s24, v239, 0
	v_readlane_b32 s25, v239, 1
	s_sub_u32 s24, s24, 0xf0
	s_subb_u32 s25, s25, 0
	s_load_dwordx2 s[26:27], s[24:25], 0x28
	s_load_dwordx2 s[28:29], s[24:25], 0xb0
	s_load_dwordx2 s[30:31], s[24:25], 0xb8
	s_load_dwordx2 s[90:91], s[24:25], 0xd0
	v_readfirstlane_b32 s0, v169
	s_lshr_b32 s0, s0, 6
	s_lshl_b32 s1, s2, 3
	s_add_i32 s0, s0, s1
	s_lshl_b32 s1, s96, 3
	v_and_b32_e32 v10, 63, v169
	v_and_b32_e32 v11, 7, v10
	v_lshrrev_b32_e32 v10, 3, v10
	s_waitcnt lgkmcnt(0)
	v_mul_u32_u24_e32 v16, 0x2c000, v11
	v_lshl_add_u32 v16, v10, 2, v16
	v_mul_u32_u24_e32 v17, 0x800, v10
	v_lshl_add_u32 v17, v11, 4, v17
	s_mov_b32 s3, 0
.Ltr_up_layer:
	s_mul_i32 s12, s3, 0x1600000
	s_add_u32 s98, s30, s12
	s_addc_u32 s99, s31, 0
	s_mul_i32 s12, s3, 0xb00000
	s_add_u32 s12, s12, 0x20c8000
	s_add_u32 s14, s54, s12
	s_addc_u32 s15, s55, 0
	s_mov_b32 s4, s0
.Ltr_up_loop:
	s_cmp_ge_u32 s4, 0x2c00
	s_cbranch_scc1 .Ltr_up_next
	s_mul_hi_u32 s6, s4, 0x5d1746
	s_mul_i32 s7, s6, 704
	s_sub_u32 s7, s4, s7
	s_mul_i32 s12, s6, 0x160000
	s_lshl_b32 s8, s7, 5
	s_add_u32 s12, s12, s8
	s_add_u32 s8, s98, s12
	s_addc_u32 s9, s99, 0
	global_load_dword v20, v16, s[8:9]
	s_add_u32 s8, s8, 0x5800
	s_addc_u32 s9, s9, 0
	global_load_dword v21, v16, s[8:9]
	s_add_u32 s8, s8, 0x5800
	s_addc_u32 s9, s9, 0
	global_load_dword v22, v16, s[8:9]
	s_add_u32 s8, s8, 0x5800
	s_addc_u32 s9, s9, 0
	global_load_dword v23, v16, s[8:9]
	s_add_u32 s8, s8, 0x5800
	s_addc_u32 s9, s9, 0
	global_load_dword v24, v16, s[8:9]
	s_add_u32 s8, s8, 0x5800
	s_addc_u32 s9, s9, 0
	global_load_dword v25, v16, s[8:9]
	s_add_u32 s8, s8, 0x5800
	s_addc_u32 s9, s9, 0
	global_load_dword v26, v16, s[8:9]
	s_add_u32 s8, s8, 0x5800
	s_addc_u32 s9, s9, 0
	global_load_dword v27, v16, s[8:9]
	s_add_u32 s13, s4, s1
	s_cmp_ge_u32 s13, 0x2c00
	s_cbranch_scc1 .Ltr_up_single
	s_mul_hi_u32 s24, s13, 0x5d1746
	s_mul_i32 s25, s24, 704
	s_sub_u32 s25, s13, s25
	s_mul_i32 s12, s24, 0x160000
	s_lshl_b32 s8, s25, 5
	s_add_u32 s12, s12, s8
	s_add_u32 s8, s98, s12
	s_addc_u32 s9, s99, 0
	global_load_dword v28, v16, s[8:9]
	s_add_u32 s8, s8, 0x5800
	s_addc_u32 s9, s9, 0
	global_load_dword v29, v16, s[8:9]
	s_add_u32 s8, s8, 0x5800
	s_addc_u32 s9, s9, 0
	global_load_dword v30, v16, s[8:9]
	s_add_u32 s8, s8, 0x5800
	s_addc_u32 s9, s9, 0
	global_load_dword v31, v16, s[8:9]
	s_add_u32 s8, s8, 0x5800
	s_addc_u32 s9, s9, 0
	global_load_dword v32, v16, s[8:9]
	s_add_u32 s8, s8, 0x5800
	s_addc_u32 s9, s9, 0
	global_load_dword v33, v16, s[8:9]
	s_add_u32 s8, s8, 0x5800
	s_addc_u32 s9, s9, 0
	global_load_dword v34, v16, s[8:9]
	s_add_u32 s8, s8, 0x5800
	s_addc_u32 s9, s9, 0
	global_load_dword v35, v16, s[8:9]
	s_waitcnt vmcnt(8)
	s_mul_i32 s12, s7, 0x4000
	s_lshl_b32 s8, s6, 7
	s_add_u32 s12, s12, s8
	v_add_u32_e32 v13, s12, v17
	v_cvt_pk_bf16_f32 v36, v20, v21
	v_cvt_pk_bf16_f32 v37, v22, v23
	v_cvt_pk_bf16_f32 v38, v24, v25
	v_cvt_pk_bf16_f32 v39, v26, v27
	global_store_dwordx4 v13, v[36:39], s[14:15]
	s_waitcnt vmcnt(1)
	s_mul_i32 s12, s25, 0x4000
	s_lshl_b32 s8, s24, 7
	s_add_u32 s12, s12, s8
	v_add_u32_e32 v15, s12, v17
	v_cvt_pk_bf16_f32 v40, v28, v29
	v_cvt_pk_bf16_f32 v41, v30, v31
	v_cvt_pk_bf16_f32 v42, v32, v33
	v_cvt_pk_bf16_f32 v43, v34, v35
	global_store_dwordx4 v15, v[40:43], s[14:15]
	s_add_u32 s4, s13, s1
	s_branch .Ltr_up_loop
.Ltr_up_single:
	s_waitcnt vmcnt(0)
	s_mul_i32 s12, s7, 0x4000
	s_lshl_b32 s8, s6, 7
	s_add_u32 s12, s12, s8
	v_add_u32_e32 v13, s12, v17
	v_cvt_pk_bf16_f32 v36, v20, v21
	v_cvt_pk_bf16_f32 v37, v22, v23
	v_cvt_pk_bf16_f32 v38, v24, v25
	v_cvt_pk_bf16_f32 v39, v26, v27
	global_store_dwordx4 v13, v[36:39], s[14:15]
.Ltr_up_next:
	s_add_i32 s3, s3, 1
	s_cmp_lt_u32 s3, 4
	s_cbranch_scc1 .Ltr_up_layer
	v_mul_u32_u24_e32 v16, 0x8000, v11
	v_lshl_add_u32 v16, v10, 2, v16
	v_mul_u32_u24_e32 v17, 0x1600, v10
	v_lshl_add_u32 v17, v11, 4, v17
	s_mov_b32 s3, 0
.Ltr_dn_layer:
	s_mul_i32 s12, s3, 0xb00000
	s_add_u32 s98, s90, s12
	s_addc_u32 s99, s91, 0
	s_mul_i32 s12, s3, 0x580000
	s_add_u32 s12, s12, 0x4cc8000
	s_add_u32 s14, s54, s12
	s_addc_u32 s15, s55, 0
	s_mov_b32 s4, s0
; DI int otid() { int t = threadIdx.x; asm volatile("" : "+v"(t)); return t; }
; DI void tr_phase(const float* __restrict__ src, int ld, int K, int N, u16* __restrict__ dst, char* smem, int& rot) {
;   float* tl = (float*)smem;
;   const int tid = otid();
;   const int KTn = K >> 5, NTn = N >> 5, ntiles = KTn * NTn;
;   int first = (int)blockIdx.x - rot;
;   if (first < 0) first += gridDim.x;
;   rot = (rot + ntiles) % (int)gridDim.x;
;   const int a = tid >> 5, bq = tid & 31;
;   for (int tile = first; tile < ntiles; tile += gridDim.x) {
;     const int kt = tile / NTn, nt = tile - kt * NTn;
;     __syncthreads();
; #pragma unroll
;     for (int i = 0; i < 2; ++i) tl[(a + 16 * i) * 33 + bq] = src[(size_t)(kt * 32 + a + 16 * i) * ld + nt * 32 + bq];
;     __syncthreads();
; #pragma unroll
;     for (int i = 0; i < 2; ++i) dst[(size_t)(nt * 32 + a + 16 * i) * K + kt * 32 + bq] = f2bf(tl[bq * 33 + a + 16 * i]);
;   }
; }
; DI void phase0(const Params& p, char* smem) {
;     ...
;     tr_phase(p.w_down + (size_t)l * 2816 * 1024, 1024, 2816, 1024, (u16*)(p.ws + WS_WDN) + (size_t)l * 1024 * 2816, smem, rot);
;     tr_phase(p.w_in + (size_t)l * 1024 * DIN, DIN, 1024, DIN, (u16*)(p.ws + WS_WIN) + (size_t)l * DINP * 1024, smem, rot);
.Ltr_dn_loop:
	s_cmp_ge_u32 s4, 0x1600
	s_cbranch_scc1 .Ltr_dn_next
	s_mul_hi_u32 s6, s4, 0x2000000
	s_mul_i32 s7, s6, 128
	s_sub_u32 s7, s4, s7
	s_mul_i32 s12, s6, 0x40000
	s_lshl_b32 s8, s7, 5
	s_add_u32 s12, s12, s8
	s_add_u32 s8, s98, s12
	s_addc_u32 s9, s99, 0
	global_load_dword v20, v16, s[8:9]
	s_add_u32 s8, s8, 0x1000
	s_addc_u32 s9, s9, 0
	global_load_dword v21, v16, s[8:9]
	s_add_u32 s8, s8, 0x1000
	s_addc_u32 s9, s9, 0
	global_load_dword v22, v16, s[8:9]
	s_add_u32 s8, s8, 0x1000
	s_addc_u32 s9, s9, 0
	global_load_dword v23, v16, s[8:9]
	s_add_u32 s8, s8, 0x1000
	s_addc_u32 s9, s9, 0
	global_load_dword v24, v16, s[8:9]
	s_add_u32 s8, s8, 0x1000
	s_addc_u32 s9, s9, 0
	global_load_dword v25, v16, s[8:9]
	s_add_u32 s8, s8, 0x1000
	s_addc_u32 s9, s9, 0
	global_load_dword v26, v16, s[8:9]
	s_add_u32 s8, s8, 0x1000
	s_addc_u32 s9, s9, 0
	global_load_dword v27, v16, s[8:9]
	s_add_u32 s13, s4, s1
	s_cmp_ge_u32 s13, 0x1600
	s_cbranch_scc1 .Ltr_dn_single
	s_mul_hi_u32 s24, s13, 0x2000000
	s_mul_i32 s25, s24, 128
	s_sub_u32 s25, s13, s25
	s_mul_i32 s12, s24, 0x40000
	s_lshl_b32 s8, s25, 5
	s_add_u32 s12, s12, s8
	s_add_u32 s8, s98, s12
	s_addc_u32 s9, s99, 0
	global_load_dword v28, v16, s[8:9]
	s_add_u32 s8, s8, 0x1000
	s_addc_u32 s9, s9, 0
	global_load_dword v29, v16, s[8:9]
	s_add_u32 s8, s8, 0x1000
	s_addc_u32 s9, s9, 0
	global_load_dword v30, v16, s[8:9]
	s_add_u32 s8, s8, 0x1000
	s_addc_u32 s9, s9, 0
	global_load_dword v31, v16, s[8:9]
	s_add_u32 s8, s8, 0x1000
	s_addc_u32 s9, s9, 0
	global_load_dword v32, v16, s[8:9]
	s_add_u32 s8, s8, 0x1000
	s_addc_u32 s9, s9, 0
	global_load_dword v33, v16, s[8:9]
	s_add_u32 s8, s8, 0x1000
	s_addc_u32 s9, s9, 0
	global_load_dword v34, v16, s[8:9]
	s_add_u32 s8, s8, 0x1000
	s_addc_u32 s9, s9, 0
	global_load_dword v35, v16, s[8:9]
	s_waitcnt vmcnt(8)
	s_mul_i32 s12, s7, 0xb000
	s_lshl_b32 s8, s6, 7
	s_add_u32 s12, s12, s8
	v_add_u32_e32 v13, s12, v17
	v_cvt_pk_bf16_f32 v36, v20, v21
	v_cvt_pk_bf16_f32 v37, v22, v23
	v_cvt_pk_bf16_f32 v38, v24, v25
	v_cvt_pk_bf16_f32 v39, v26, v27
	global_store_dwordx4 v13, v[36:39], s[14:15]
	s_waitcnt vmcnt(1)
	s_mul_i32 s12, s25, 0xb000
	s_lshl_b32 s8, s24, 7
	s_add_u32 s12, s12, s8
	v_add_u32_e32 v15, s12, v17
	v_cvt_pk_bf16_f32 v40, v28, v29
	v_cvt_pk_bf16_f32 v41, v30, v31
	v_cvt_pk_bf16_f32 v42, v32, v33
	v_cvt_pk_bf16_f32 v43, v34, v35
	global_store_dwordx4 v15, v[40:43], s[14:15]
	s_add_u32 s4, s13, s1
	s_branch .Ltr_dn_loop
.Ltr_dn_single:
	s_waitcnt vmcnt(0)
	s_mul_i32 s12, s7, 0xb000
	s_lshl_b32 s8, s6, 7
	s_add_u32 s12, s12, s8
	v_add_u32_e32 v13, s12, v17
	v_cvt_pk_bf16_f32 v36, v20, v21
	v_cvt_pk_bf16_f32 v37, v22, v23
	v_cvt_pk_bf16_f32 v38, v24, v25
	v_cvt_pk_bf16_f32 v39, v26, v27
	global_store_dwordx4 v13, v[36:39], s[14:15]
.Ltr_dn_next:
	s_add_i32 s3, s3, 1
	s_cmp_lt_u32 s3, 4
	s_cbranch_scc1 .Ltr_dn_layer
	v_mul_u32_u24_e32 v16, 0x12800, v11
	v_lshl_add_u32 v16, v10, 2, v16
	v_mul_u32_u24_e32 v17, 0x800, v10
	v_lshl_add_u32 v17, v11, 4, v17
	s_mov_b32 s3, 0
.Ltr_in_layer:
	s_mul_i32 s12, s3, 0x940000
	s_add_u32 s98, s26, s12
	s_addc_u32 s99, s27, 0
	s_mul_i32 s12, s3, 0x500000
	s_add_u32 s12, s12, 0xc8000
	s_add_u32 s14, s54, s12
	s_addc_u32 s15, s55, 0
	s_mov_b32 s4, s0
.Ltr_in_loop:
	s_cmp_ge_u32 s4, 0x1280
	s_cbranch_scc1 .Ltr_in_next
	s_mul_hi_u32 s6, s4, 0xdd67c9
	s_mul_i32 s7, s6, 296
	s_sub_u32 s7, s4, s7
	s_mul_i32 s12, s6, 0x94000
	s_lshl_b32 s8, s7, 5
	s_add_u32 s12, s12, s8
	s_add_u32 s8, s98, s12
	s_addc_u32 s9, s99, 0
	global_load_dword v20, v16, s[8:9]
	s_add_u32 s8, s8, 0x2500
	s_addc_u32 s9, s9, 0
	global_load_dword v21, v16, s[8:9]
	s_add_u32 s8, s8, 0x2500
	s_addc_u32 s9, s9, 0
	global_load_dword v22, v16, s[8:9]
	s_add_u32 s8, s8, 0x2500
	s_addc_u32 s9, s9, 0
	global_load_dword v23, v16, s[8:9]
	s_add_u32 s8, s8, 0x2500
	s_addc_u32 s9, s9, 0
	global_load_dword v24, v16, s[8:9]
	s_add_u32 s8, s8, 0x2500
	s_addc_u32 s9, s9, 0
	global_load_dword v25, v16, s[8:9]
	s_add_u32 s8, s8, 0x2500
	s_addc_u32 s9, s9, 0
	global_load_dword v26, v16, s[8:9]
	s_add_u32 s8, s8, 0x2500
	s_addc_u32 s9, s9, 0
	global_load_dword v27, v16, s[8:9]
	s_add_u32 s13, s4, s1
	s_cmp_ge_u32 s13, 0x1280
	s_cbranch_scc1 .Ltr_in_single
	s_mul_hi_u32 s24, s13, 0xdd67c9
	s_mul_i32 s25, s24, 296
	s_sub_u32 s25, s13, s25
	s_mul_i32 s12, s24, 0x94000
	s_lshl_b32 s8, s25, 5
	s_add_u32 s12, s12, s8
	s_add_u32 s8, s98, s12
	s_addc_u32 s9, s99, 0
	global_load_dword v28, v16, s[8:9]
	s_add_u32 s8, s8, 0x2500
	s_addc_u32 s9, s9, 0
	global_load_dword v29, v16, s[8:9]
	s_add_u32 s8, s8, 0x2500
	s_addc_u32 s9, s9, 0
	global_load_dword v30, v16, s[8:9]
	s_add_u32 s8, s8, 0x2500
	s_addc_u32 s9, s9, 0
	global_load_dword v31, v16, s[8:9]
	s_add_u32 s8, s8, 0x2500
	s_addc_u32 s9, s9, 0
	global_load_dword v32, v16, s[8:9]
	s_add_u32 s8, s8, 0x2500
	s_addc_u32 s9, s9, 0
	global_load_dword v33, v16, s[8:9]
	s_add_u32 s8, s8, 0x2500
	s_addc_u32 s9, s9, 0
	global_load_dword v34, v16, s[8:9]
	s_add_u32 s8, s8, 0x2500
	s_addc_u32 s9, s9, 0
	global_load_dword v35, v16, s[8:9]
	s_waitcnt vmcnt(8)
	s_mul_i32 s12, s7, 0x4000
	s_lshl_b32 s8, s6, 7
	s_add_u32 s12, s12, s8
	v_add_u32_e32 v13, s12, v17
	v_cvt_pk_bf16_f32 v36, v20, v21
	v_cvt_pk_bf16_f32 v37, v22, v23
	v_cvt_pk_bf16_f32 v38, v24, v25
	v_cvt_pk_bf16_f32 v39, v26, v27
	global_store_dwordx4 v13, v[36:39], s[14:15]
	s_waitcnt vmcnt(1)
	s_mul_i32 s12, s25, 0x4000
	s_lshl_b32 s8, s24, 7
	s_add_u32 s12, s12, s8
	v_add_u32_e32 v15, s12, v17
	v_cvt_pk_bf16_f32 v40, v28, v29
	v_cvt_pk_bf16_f32 v41, v30, v31
	v_cvt_pk_bf16_f32 v42, v32, v33
	v_cvt_pk_bf16_f32 v43, v34, v35
	global_store_dwordx4 v15, v[40:43], s[14:15]
	s_add_u32 s4, s13, s1
	s_branch .Ltr_in_loop

; DI int otid() { int t = threadIdx.x; asm volatile("" : "+v"(t)); return t; }
; DI void tr_phase(const float* __restrict__ src, int ld, int K, int N, u16* __restrict__ dst, char* smem, int& rot) {
;   float* tl = (float*)smem;
;   const int tid = otid();
;   const int KTn = K >> 5, NTn = N >> 5, ntiles = KTn * NTn;
;   int first = (int)blockIdx.x - rot;
;   if (first < 0) first += gridDim.x;
;   rot = (rot + ntiles) % (int)gridDim.x;
;   const int a = tid >> 5, bq = tid & 31;
;   for (int tile = first; tile < ntiles; tile += gridDim.x) {
;     const int kt = tile / NTn, nt = tile - kt * NTn;
;     __syncthreads();
; #pragma unroll
;     for (int i = 0; i < 2; ++i) tl[(a + 16 * i) * 33 + bq] = src[(size_t)(kt * 32 + a + 16 * i) * ld + nt * 32 + bq];
;     __syncthreads();
; #pragma unroll
;     for (int i = 0; i < 2; ++i) dst[(size_t)(nt * 32 + a + 16 * i) * K + kt * 32 + bq] = f2bf(tl[bq * 33 + a + 16 * i]);
;   }
; }
; DI void phase0(const Params& p, char* smem) {
;     ...
;     tr_phase(p.w_in + (size_t)l * 1024 * DIN, DIN, 1024, DIN, (u16*)(p.ws + WS_WIN) + (size_t)l * DINP * 1024, smem, rot);
;     tr_phase(p.w_out + (size_t)l * 1024 * 1024, 1024, 1024, 1024, (u16*)(p.ws + WS_WOUT) + (size_t)l * 1024 * 1024, smem, rot);
.Ltr_in_next:
	s_add_i32 s3, s3, 1
	s_cmp_lt_u32 s3, 4
	s_cbranch_scc1 .Ltr_in_layer
	v_mul_u32_u24_e32 v16, 0x8000, v11
	v_lshl_add_u32 v16, v10, 2, v16
	v_mul_u32_u24_e32 v17, 0x800, v10
	v_lshl_add_u32 v17, v11, 4, v17
	s_mov_b32 s3, 0
.Ltr_out_layer:
	s_mul_i32 s12, s3, 0x400000
	s_add_u32 s98, s28, s12
	s_addc_u32 s99, s29, 0
	s_mul_i32 s12, s3, 0x200000
	s_add_u32 s12, s12, 0x18c8000
	s_add_u32 s14, s54, s12
	s_addc_u32 s15, s55, 0
	s_mov_b32 s4, s0
.Ltr_out_loop:
	s_cmp_ge_u32 s4, 0x800
	s_cbranch_scc1 .Ltr_out_next
	s_mul_hi_u32 s6, s4, 0x2000000
	s_mul_i32 s7, s6, 128
	s_sub_u32 s7, s4, s7
	s_mul_i32 s12, s6, 0x40000
	s_lshl_b32 s8, s7, 5
	s_add_u32 s12, s12, s8
	s_add_u32 s8, s98, s12
	s_addc_u32 s9, s99, 0
	global_load_dword v20, v16, s[8:9]
	s_add_u32 s8, s8, 0x1000
	s_addc_u32 s9, s9, 0
	global_load_dword v21, v16, s[8:9]
	s_add_u32 s8, s8, 0x1000
	s_addc_u32 s9, s9, 0
	global_load_dword v22, v16, s[8:9]
	s_add_u32 s8, s8, 0x1000
	s_addc_u32 s9, s9, 0
	global_load_dword v23, v16, s[8:9]
	s_add_u32 s8, s8, 0x1000
	s_addc_u32 s9, s9, 0
	global_load_dword v24, v16, s[8:9]
	s_add_u32 s8, s8, 0x1000
	s_addc_u32 s9, s9, 0
	global_load_dword v25, v16, s[8:9]
	s_add_u32 s8, s8, 0x1000
	s_addc_u32 s9, s9, 0
	global_load_dword v26, v16, s[8:9]
	s_add_u32 s8, s8, 0x1000
	s_addc_u32 s9, s9, 0
	global_load_dword v27, v16, s[8:9]
	s_add_u32 s13, s4, s1
	s_cmp_ge_u32 s13, 0x800
	s_cbranch_scc1 .Ltr_out_single
	s_mul_hi_u32 s24, s13, 0x2000000
	s_mul_i32 s25, s24, 128
	s_sub_u32 s25, s13, s25
	s_mul_i32 s12, s24, 0x40000
	s_lshl_b32 s8, s25, 5
	s_add_u32 s12, s12, s8
	s_add_u32 s8, s98, s12
	s_addc_u32 s9, s99, 0
	global_load_dword v28, v16, s[8:9]
	s_add_u32 s8, s8, 0x1000
	s_addc_u32 s9, s9, 0
	global_load_dword v29, v16, s[8:9]
	s_add_u32 s8, s8, 0x1000
	s_addc_u32 s9, s9, 0
	global_load_dword v30, v16, s[8:9]
	s_add_u32 s8, s8, 0x1000
	s_addc_u32 s9, s9, 0
	global_load_dword v31, v16, s[8:9]
	s_add_u32 s8, s8, 0x1000
	s_addc_u32 s9, s9, 0
	global_load_dword v32, v16, s[8:9]
	s_add_u32 s8, s8, 0x1000
	s_addc_u32 s9, s9, 0
	global_load_dword v33, v16, s[8:9]
	s_add_u32 s8, s8, 0x1000
	s_addc_u32 s9, s9, 0
	global_load_dword v34, v16, s[8:9]
	s_add_u32 s8, s8, 0x1000
	s_addc_u32 s9, s9, 0
	global_load_dword v35, v16, s[8:9]
	s_waitcnt vmcnt(8)
	s_mul_i32 s12, s7, 0x4000
	s_lshl_b32 s8, s6, 7
	s_add_u32 s12, s12, s8
	v_add_u32_e32 v13, s12, v17
	v_cvt_pk_bf16_f32 v36, v20, v21
	v_cvt_pk_bf16_f32 v37, v22, v23
	v_cvt_pk_bf16_f32 v38, v24, v25
	v_cvt_pk_bf16_f32 v39, v26, v27
	global_store_dwordx4 v13, v[36:39], s[14:15]
	s_waitcnt vmcnt(1)
	s_mul_i32 s12, s25, 0x4000
	s_lshl_b32 s8, s24, 7
	s_add_u32 s12, s12, s8
	v_add_u32_e32 v15, s12, v17
	v_cvt_pk_bf16_f32 v40, v28, v29
	v_cvt_pk_bf16_f32 v41, v30, v31
	v_cvt_pk_bf16_f32 v42, v32, v33
	v_cvt_pk_bf16_f32 v43, v34, v35
	global_store_dwordx4 v15, v[40:43], s[14:15]
	s_add_u32 s4, s13, s1
	s_branch .Ltr_out_loop

; DI void phase0(const Params& p, char* smem) {
;     ...
;   int rot = 0;
;   for (int l = 0; l < NLAYER; ++l) {
;     tr_phase(p.w_up + (size_t)l * 1024 * 5632, 5632, 1024, 5632, (u16*)(p.ws + WS_WUP) + (size_t)l * 5632 * 1024, smem, rot);
.Ltr_out_next:
	s_add_i32 s3, s3, 1
	s_cmp_lt_u32 s3, 4
	s_cbranch_scc1 .Ltr_out_layer
	s_add_u32 s24, s54, 0x20c8000
	s_addc_u32 s25, s55, 0
	s_add_u32 s26, s54, 0x4cc8000
	s_addc_u32 s28, s55, 0
	s_add_u32 s0, s54, 0xc8000
	v_writelane_b32 v239, s0, 51
	s_addc_u32 s0, s55, 0
	s_add_u32 s29, s54, 0x18c8000
	s_addc_u32 s30, s55, 0
	s_add_u32 s6, s54, 0x1648000
	s_addc_u32 s7, s55, 0
	s_add_u32 s31, s54, 0x1848000
	s_addc_u32 s33, s55, 0
	s_add_u32 s90, s54, 0x1748000
	s_addc_u32 s91, s55, 0
	s_add_u32 s92, s54, 0x17c8000
	v_writelane_b32 v239, s0, 52
	s_addc_u32 s0, s55, 0
	s_abs_i32 s3, s96
	v_cvt_f32_u32_e32 v1, s3
	v_writelane_b32 v239, s0, 53
	s_sub_i32 s0, 0, s3
	s_mov_b32 s1, 0
	v_rcp_iflag_f32_e32 v1, v1
	v_mov_b32_e32 v3, 0
	s_movk_i32 s8, 0x84
	s_movk_i32 s9, 0x5800
	v_mul_f32_e32 v1, 0x4f7ffffe, v1
	v_cvt_u32_f32_e32 v1, v1
	s_movk_i32 s13, 0x1600
	s_movk_i32 s14, 0x2500
	s_lshl_b32 s12, s96, 5
	v_readfirstlane_b32 s4, v1
	s_mul_i32 s0, s0, s4
	s_mul_hi_u32 s0, s4, s0
	s_add_i32 s27, s4, s0
	s_mov_b32 s0, s1
	s_mov_b32 s15, s1
	s_branch .LBB0_25

; DI int otid() { int t = threadIdx.x; asm volatile("" : "+v"(t)); return t; }
; DI void tr_phase(const float* __restrict__ src, int ld, int K, int N, u16* __restrict__ dst, char* smem, int& rot) {
;   float* tl = (float*)smem;
;   const int tid = otid();
;   const int KTn = K >> 5, NTn = N >> 5, ntiles = KTn * NTn;
;   int first = (int)blockIdx.x - rot;
;   if (first < 0) first += gridDim.x;
;   rot = (rot + ntiles) % (int)gridDim.x;
;   const int a = tid >> 5, bq = tid & 31;
;   for (int tile = first; tile < ntiles; tile += gridDim.x) {
; DI void phase0(const Params& p, char* smem) {
;     ...
;     tr_phase(p.w_up + (size_t)l * 1024 * 5632, 5632, 1024, 5632, (u16*)(p.ws + WS_WUP) + (size_t)l * 5632 * 1024, smem, rot);
.LBB0_25:
	s_sub_i32 s16, s2, s15
	s_ashr_i32 s17, s16, 31
	s_and_b32 s17, s17, s96
	s_add_i32 s16, s17, s16
	s_mul_hi_u32 s4, s0, 0xb00000
	s_mul_i32 s5, s0, 0xb00000
	v_mov_b32_e32 v2, v169
	s_cmpk_gt_i32 s16, 0x8000
	s_cbranch_scc1 .LBB0_28
	s_add_u32 s18, s24, s5
	v_readlane_b32 s56, v239, 35
	s_addc_u32 s19, s25, s4
	s_mul_i32 s20, s0, 0x1600000
	v_readlane_b32 s70, v239, 49
	s_mul_hi_u32 s17, s0, 0x1600000
	v_readlane_b32 s71, v239, 50
	s_add_u32 s20, s70, s20
	v_and_b32_e32 v6, 31, v2
	v_ashrrev_i32_e32 v1, 5, v2
	s_addc_u32 s21, s71, s17
	v_lshlrev_b32_e32 v2, 2, v6
	v_lshl_add_u64 v[4:5], s[20:21], 0, v[2:3]
	v_add_u32_e32 v9, 0, v2
	v_lshlrev_b32_e32 v2, 1, v6
	v_lshl_add_u32 v8, v1, 2, 0
	v_mul_u32_u24_e32 v10, 0x84, v6
	v_lshl_add_u64 v[6:7], s[18:19], 0, v[2:3]
	v_mul_lo_u32 v2, v1, s8
	s_lshl_b32 s17, s16, 5
	v_add_u32_e32 v2, v9, v2
	v_add_u32_e32 v8, v8, v10
	v_readlane_b32 s57, v239, 36
	v_readlane_b32 s58, v239, 37
	v_readlane_b32 s59, v239, 38
	v_readlane_b32 s60, v239, 39
	v_readlane_b32 s61, v239, 40
	v_readlane_b32 s62, v239, 41
	v_readlane_b32 s63, v239, 42
	v_readlane_b32 s64, v239, 43
	v_readlane_b32 s65, v239, 44
	v_readlane_b32 s66, v239, 45
	v_readlane_b32 s67, v239, 46
	v_readlane_b32 s68, v239, 47
	v_readlane_b32 s69, v239, 48

; DI void tr_phase(const float* __restrict__ src, int ld, int K, int N, u16* __restrict__ dst, char* smem, int& rot) {
;     ...
;   const int KTn = K >> 5, NTn = N >> 5, ntiles = KTn * NTn;
;   int first = (int)blockIdx.x - rot;
;   if (first < 0) first += gridDim.x;
;   rot = (rot + ntiles) % (int)gridDim.x;
;   const int a = tid >> 5, bq = tid & 31;
;   for (int tile = first; tile < ntiles; tile += gridDim.x) {
; DI void phase0(const Params& p, char* smem) {
;     ...
;     tr_phase(p.w_down + (size_t)l * 2816 * 1024, 1024, 2816, 1024, (u16*)(p.ws + WS_WDN) + (size_t)l * 1024 * 2816, smem, rot);
.LBB0_28:
	s_addk_i32 s15, 0x1600
	s_ashr_i32 s16, s15, 31
	s_abs_i32 s15, s15
	s_mul_hi_u32 s17, s15, s27
	s_mul_i32 s17, s17, s3
	s_sub_i32 s15, s15, s17
	s_sub_i32 s17, s15, s3
	s_cmp_ge_u32 s15, s3
	s_cselect_b32 s15, s17, s15
	s_sub_i32 s17, s15, s3
	s_cmp_ge_u32 s15, s3
	s_cselect_b32 s15, s17, s15
	s_xor_b32 s15, s15, s16
	s_sub_i32 s15, s15, s16
	s_sub_i32 s16, s2, s15
	s_ashr_i32 s17, s16, 31
	s_and_b32 s17, s17, s96
	s_add_i32 s16, s17, s16
	v_mov_b32_e32 v2, v169
	s_cmpk_gt_i32 s16, 0x8000
	s_cbranch_scc1 .LBB0_31
	s_mul_i32 s18, s0, 0x580000
	s_mul_hi_u32 s17, s0, 0x580000
	s_add_u32 s18, s26, s18
	s_addc_u32 s19, s28, s17
	s_add_u32 s20, s40, s5
	v_and_b32_e32 v6, 31, v2
	v_ashrrev_i32_e32 v1, 5, v2
	s_addc_u32 s21, s41, s4
	v_lshlrev_b32_e32 v2, 2, v6
	v_lshl_add_u64 v[4:5], s[20:21], 0, v[2:3]
	v_add_u32_e32 v9, 0, v2
	v_lshlrev_b32_e32 v2, 1, v6
	v_lshl_add_u32 v8, v1, 2, 0
	v_mul_u32_u24_e32 v10, 0x84, v6
	v_lshl_add_u64 v[6:7], s[18:19], 0, v[2:3]
	v_mul_lo_u32 v2, v1, s8
	s_lshl_b32 s4, s16, 5
	v_add_u32_e32 v2, v9, v2
	v_add_u32_e32 v8, v8, v10

; DI void tr_phase(const float* __restrict__ src, int ld, int K, int N, u16* __restrict__ dst, char* smem, int& rot) {
;     ...
;   const int KTn = K >> 5, NTn = N >> 5, ntiles = KTn * NTn;
;   int first = (int)blockIdx.x - rot;
;   if (first < 0) first += gridDim.x;
;   rot = (rot + ntiles) % (int)gridDim.x;
;   const int a = tid >> 5, bq = tid & 31;
;   for (int tile = first; tile < ntiles; tile += gridDim.x) {
; DI void phase0(const Params& p, char* smem) {
;     ...
;     tr_phase(p.w_in + (size_t)l * 1024 * DIN, DIN, 1024, DIN, (u16*)(p.ws + WS_WIN) + (size_t)l * DINP * 1024, smem, rot);
.LBB0_31:
	s_addk_i32 s15, 0xb00
	s_abs_i32 s5, s15
	s_ashr_i32 s4, s15, 31
	s_mul_hi_u32 s15, s5, s27
	s_mul_i32 s15, s15, s3
	s_sub_i32 s5, s5, s15
	s_sub_i32 s15, s5, s3
	s_cmp_ge_u32 s5, s3
	s_cselect_b32 s5, s15, s5
	s_sub_i32 s15, s5, s3
	s_cmp_ge_u32 s5, s3
	s_cselect_b32 s5, s15, s5
	s_xor_b32 s5, s5, s4
	s_sub_i32 s4, s5, s4
	s_sub_i32 s5, s2, s4
	s_ashr_i32 s15, s5, 31
	s_and_b32 s15, s15, s96
	s_add_i32 s5, s15, s5
	v_mov_b32_e32 v2, v169
	s_cmpk_gt_i32 s5, 0x8000
	s_cbranch_scc1 .LBB0_34
	s_mul_i32 s16, s0, 0x500000
	v_readlane_b32 s17, v239, 51
	s_mul_hi_u32 s15, s0, 0x500000
	s_add_u32 s16, s17, s16
	v_readlane_b32 s17, v239, 52
	v_readlane_b32 s56, v239, 2
	s_addc_u32 s17, s17, s15
	s_mul_i32 s18, s0, 0x940000
	v_readlane_b32 s66, v239, 12
	s_mul_hi_u32 s15, s0, 0x940000
	v_readlane_b32 s67, v239, 13
	s_add_u32 s18, s66, s18
	v_and_b32_e32 v6, 31, v2
	v_ashrrev_i32_e32 v1, 5, v2
	s_addc_u32 s19, s67, s15
	v_lshlrev_b32_e32 v2, 2, v6
	v_lshl_add_u64 v[4:5], s[18:19], 0, v[2:3]
	v_add_u32_e32 v9, 0, v2
	v_lshlrev_b32_e32 v2, 1, v6
	v_lshl_add_u32 v8, v1, 2, 0
	v_mul_u32_u24_e32 v10, 0x84, v6
	v_lshl_add_u64 v[6:7], s[16:17], 0, v[2:3]
	v_mul_lo_u32 v2, v1, s8
	s_lshl_b32 s15, s5, 5
	v_add_u32_e32 v2, v9, v2
	v_add_u32_e32 v8, v8, v10
	v_readlane_b32 s57, v239, 3
	v_readlane_b32 s58, v239, 4
	v_readlane_b32 s59, v239, 5
	v_readlane_b32 s60, v239, 6
	v_readlane_b32 s61, v239, 7
	v_readlane_b32 s62, v239, 8
	v_readlane_b32 s63, v239, 9
	v_readlane_b32 s64, v239, 10
	v_readlane_b32 s65, v239, 11
	v_readlane_b32 s68, v239, 14
	v_readlane_b32 s69, v239, 15
	v_readlane_b32 s70, v239, 16
	v_readlane_b32 s71, v239, 17

; DI void tr_phase(const float* __restrict__ src, int ld, int K, int N, u16* __restrict__ dst, char* smem, int& rot) {
;     ...
;   const int KTn = K >> 5, NTn = N >> 5, ntiles = KTn * NTn;
;   int first = (int)blockIdx.x - rot;
;   if (first < 0) first += gridDim.x;
;   rot = (rot + ntiles) % (int)gridDim.x;
;   const int a = tid >> 5, bq = tid & 31;
;   for (int tile = first; tile < ntiles; tile += gridDim.x) {
; DI void phase0(const Params& p, char* smem) {
;     ...
;     tr_phase(p.w_out + (size_t)l * 1024 * 1024, 1024, 1024, 1024, (u16*)(p.ws + WS_WOUT) + (size_t)l * 1024 * 1024, smem, rot);
.LBB0_34:
	s_addk_i32 s4, 0x940
	s_ashr_i32 s5, s4, 31
	s_abs_i32 s4, s4
	s_mul_hi_u32 s15, s4, s27
	s_mul_i32 s15, s15, s3
	s_sub_i32 s4, s4, s15
	s_sub_i32 s15, s4, s3
	s_cmp_ge_u32 s4, s3
	s_cselect_b32 s4, s15, s4
	s_sub_i32 s15, s4, s3
	s_cmp_ge_u32 s4, s3
	s_cselect_b32 s4, s15, s4
	s_xor_b32 s4, s4, s5
	s_sub_i32 s4, s4, s5
	s_sub_i32 s5, s2, s4
	s_ashr_i32 s15, s5, 31
	s_and_b32 s15, s15, s96
	s_add_i32 s5, s15, s5
	v_mov_b32_e32 v2, v169
	s_cmpk_gt_i32 s5, 0x8000
	s_cbranch_scc1 .LBB0_37
	s_lshl_b64 s[16:17], s[0:1], 21
	s_add_u32 s16, s29, s16
	v_readlane_b32 s56, v239, 35
	s_addc_u32 s17, s30, s17
	s_lshl_b64 s[18:19], s[0:1], 22
	v_readlane_b32 s68, v239, 47
	v_readlane_b32 s69, v239, 48
	s_add_u32 s18, s68, s18
	v_and_b32_e32 v6, 31, v2
	v_ashrrev_i32_e32 v1, 5, v2
	s_addc_u32 s19, s69, s19
	v_lshlrev_b32_e32 v2, 2, v6
	v_lshl_add_u64 v[4:5], s[18:19], 0, v[2:3]
	v_add_u32_e32 v9, 0, v2
	v_lshlrev_b32_e32 v2, 1, v6
	v_lshl_add_u32 v8, v1, 2, 0
	v_mul_u32_u24_e32 v10, 0x84, v6
	v_lshl_add_u64 v[6:7], s[16:17], 0, v[2:3]
	v_mul_lo_u32 v2, v1, s8
	s_lshl_b32 s15, s5, 5
	v_add_u32_e32 v2, v9, v2
	v_add_u32_e32 v8, v8, v10
	v_readlane_b32 s57, v239, 36
	v_readlane_b32 s58, v239, 37
	v_readlane_b32 s59, v239, 38
	v_readlane_b32 s60, v239, 39
	v_readlane_b32 s61, v239, 40
	v_readlane_b32 s62, v239, 41
	v_readlane_b32 s63, v239, 42
	v_readlane_b32 s64, v239, 43
	v_readlane_b32 s65, v239, 44
	v_readlane_b32 s66, v239, 45
	v_readlane_b32 s67, v239, 46
	v_readlane_b32 s70, v239, 49
	v_readlane_b32 s71, v239, 50
